# grid barriers: the per-CU L1 invalidate is issued before the arrival atomic (no vector loads happen between arrival and barrier exit) instead of after the generation flag flips; otherwise v69
# speedup vs baseline: 1.0297x; 1.0063x over previous
; __device__ __forceinline__ unsigned xb_add(unsigned* p, unsigned v) { return __hip_atomic_fetch_add(p, v, __ATOMIC_RELAXED, __HIP_MEMORY_SCOPE_AGENT); }
; __device__ __forceinline__ void xcd_barrier(const XcdBarrier& b) {
;     ...
;     if (threadIdx.x == 0) {
;         unsigned* bar = b.bar;
;         __builtin_amdgcn_s_waitcnt(0);
;         unsigned nloc = b.st[0], nx = b.st[1];
;         if (nloc == 0u) { xcd_barrier_complete(bar, b.x, nloc, nx); b.st[0] = nloc; b.st[1] = nx; }
;         const unsigned old = xb_add(&bar[XB_XSUB(b.x)], 1u);
.LBB0_65:
	s_mov_b64 s[6:7], exec
	s_lshl_b32 s4, s3, 8
	v_mbcnt_lo_u32_b32 v1, s6, 0
	s_add_u32 s4, s18, s4
	v_mbcnt_hi_u32_b32 v1, s7, v1
	s_addc_u32 s5, s19, 0
	v_cmp_eq_u32_e32 vcc, 0, v1
	s_and_saveexec_b64 s[8:9], vcc
	s_cbranch_execz .LBB0_67
	s_bcnt1_i32_b64 s6, s[6:7]
	v_mov_b32_e32 v3, 0x1000
	v_mov_b32_e32 v4, s6
	buffer_inv sc1
	global_atomic_add v3, v3, v4, s[4:5] offset:1024 sc0

; __device__ __forceinline__ unsigned xb_ld(unsigned* p)              { return __hip_atomic_load(p, __ATOMIC_RELAXED, __HIP_MEMORY_SCOPE_AGENT); }
; #define XB_SPIN(cond, bar) do { unsigned _sp = 0; while (cond) { __builtin_amdgcn_s_sleep(1); \
;     if ((++_sp & 255u) == 0u) { if (xb_ld(&(bar)[XB_TMO])) break; if (_sp > XB_SPIN_CAP) { atomicAdd(&(bar)[XB_TMO], 1u); break; } } } } while (0)
; __device__ __forceinline__ void xcd_barrier(const XcdBarrier& b) {
;     ...
;             XB_SPIN(xb_ld(&bar[XB_XGEN(b.x)]) == gen, bar);
;             __builtin_amdgcn_fence(__ATOMIC_ACQUIRE, "agent");
;             asm volatile("s_waitcnt vmcnt(0)" ::: "memory");
.LBB0_80:
	s_or_b64 exec, exec, s[8:9]
	s_waitcnt vmcnt(0)
	s_waitcnt vmcnt(0)

; __device__ __forceinline__ unsigned xb_add(unsigned* p, unsigned v) { return __hip_atomic_fetch_add(p, v, __ATOMIC_RELAXED, __HIP_MEMORY_SCOPE_AGENT); }
; __device__ __forceinline__ void xcd_barrier(const XcdBarrier& b) {
;     ...
;             __builtin_amdgcn_fence(__ATOMIC_ACQUIRE, "agent");
;             xb_add(&bar[XB_XGEN(b.x)], 1u);
;             asm volatile("s_waitcnt vmcnt(0)" ::: "memory");
.LBB0_98:
	s_or_b64 exec, exec, s[6:7]
	s_mov_b64 s[6:7], exec
	v_mbcnt_lo_u32_b32 v0, s6, 0
	v_mbcnt_hi_u32_b32 v0, s7, v0
	v_cmp_eq_u32_e32 vcc, 0, v0
	s_waitcnt vmcnt(0)
	s_and_saveexec_b64 s[8:9], vcc
	s_cbranch_execz .LBB0_100
	s_bcnt1_i32_b64 s6, s[6:7]
	v_mov_b32_e32 v0, 0x2000
	v_mov_b32_e32 v1, s6
	global_atomic_add v0, v1, s[4:5] offset:1024

; __device__ __forceinline__ unsigned xb_add(unsigned* p, unsigned v) { return __hip_atomic_fetch_add(p, v, __ATOMIC_RELAXED, __HIP_MEMORY_SCOPE_AGENT); }
; __device__ __forceinline__ void xcd_barrier(const XcdBarrier& b) {
;     ...
;     if (threadIdx.x == 0) {
;         unsigned* bar = b.bar;
;         __builtin_amdgcn_s_waitcnt(0);
;         unsigned nloc = b.st[0], nx = b.st[1];
;         if (nloc == 0u) { xcd_barrier_complete(bar, b.x, nloc, nx); b.st[0] = nloc; b.st[1] = nx; }
;         const unsigned old = xb_add(&bar[XB_XSUB(b.x)], 1u);
.LBB0_1276:
	s_mov_b64 s[6:7], exec
	s_lshl_b32 s3, s3, 8
	v_mbcnt_lo_u32_b32 v1, s6, 0
	s_add_u32 s4, s18, s3
	v_mbcnt_hi_u32_b32 v1, s7, v1
	s_addc_u32 s5, s19, 0
	v_cmp_eq_u32_e32 vcc, 0, v1
	s_and_saveexec_b64 s[8:9], vcc
	s_cbranch_execz .LBB0_1278
	s_bcnt1_i32_b64 s3, s[6:7]
	v_mov_b32_e32 v3, 0x1000
	v_mov_b32_e32 v4, s3
	buffer_inv sc1
	global_atomic_add v3, v3, v4, s[4:5] offset:1024 sc0

; __device__ __forceinline__ unsigned xb_add(unsigned* p, unsigned v) { return __hip_atomic_fetch_add(p, v, __ATOMIC_RELAXED, __HIP_MEMORY_SCOPE_AGENT); }
; __device__ __forceinline__ void xcd_barrier(const XcdBarrier& b) {
;     ...
;             __builtin_amdgcn_fence(__ATOMIC_ACQUIRE, "agent");
;             xb_add(&bar[XB_XGEN(b.x)], 1u);
;             asm volatile("s_waitcnt vmcnt(0)" ::: "memory");
.LBB0_1309:
	s_or_b64 exec, exec, s[6:7]
	s_mov_b64 s[6:7], exec
	v_mbcnt_lo_u32_b32 v0, s6, 0
	v_mbcnt_hi_u32_b32 v0, s7, v0
	v_cmp_eq_u32_e32 vcc, 0, v0
	s_waitcnt vmcnt(0)
	s_and_saveexec_b64 s[8:9], vcc
	s_cbranch_execz .LBB0_1311
	s_bcnt1_i32_b64 s3, s[6:7]
	v_mov_b32_e32 v0, 0x2000
	v_mov_b32_e32 v1, s3
	global_atomic_add v0, v1, s[4:5] offset:1024
